# speedup vs baseline: 1.0027x; 1.0027x over previous
; DEVI void finishSM(f32x16& p0, f32x16& p1, float alpha, float& l_reg, bf16x8& pa0, bf16x8& pa1, bf16x8& pa2, bf16x8& pa3) {
; #pragma unroll
;   for (int r = 0; r < 16; ++r) p1[r] = __builtin_amdgcn_exp2f(p1[r]);
;   float ps = 0;
; #pragma unroll
;   for (int r = 0; r < 16; ++r) ps += p0[r];
; #pragma unroll
;   for (int r = 0; r < 16; ++r) ps += p1[r];
;   { auto rr = __builtin_amdgcn_permlane32_swap(__float_as_uint(ps), __float_as_uint(ps), false, false);
;     ps = __uint_as_float(rr[0]) + __uint_as_float(rr[1]); }
;   l_reg = l_reg * alpha + ps;
;     ...
;   PK4(p0, 0, pa0); PK4(p0, 8, pa1); PK4(p1, 0, pa2); PK4(p1, 8, pa3);
; DEVI void qkt(f32x16& p0, f32x16& p1, const char* Ks, const char* Rs, const bf16x8* qr, const char* Qrs, int r32, int hi) {
;   p0 = f32x16{}; p1 = f32x16{};
; #pragma unroll
;   for (int d0 = 0; d0 < 8; ++d0) { int cb = (d0 * 16 + hi * 8) * 2;
;     bf16x8 b0 = *reinterpret_cast<const bf16x8*>(Ks + KSWZ(r32, cb));
;     bf16x8 b1 = *reinterpret_cast<const bf16x8*>(Ks + KSWZ(32 + r32, cb));
;     p0 = __builtin_amdgcn_mfma_f32_32x32x16_bf16(b0, qr[d0], p0, 0, 0, 0);
;     p1 = __builtin_amdgcn_mfma_f32_32x32x16_bf16(b1, qr[d0], p1, 0, 0, 0); }
; #pragma unroll
;   for (int d0 = 0; d0 < 4; ++d0) { int cb = (d0 * 16 + hi * 8) * 2;
;     bf16x8 b0 = *reinterpret_cast<const bf16x8*>(Rs + RSWZ(r32, cb));
;     bf16x8 b1 = *reinterpret_cast<const bf16x8*>(Rs + RSWZ(32 + r32, cb));
;     bf16x8 qf = *reinterpret_cast<const bf16x8*>(Qrs + RSWZ(r32, cb));
;     p0 = __builtin_amdgcn_mfma_f32_32x32x16_bf16(b0, qf, p0, 0, 0, 0);
;     p1 = __builtin_amdgcn_mfma_f32_32x32x16_bf16(b1, qf, p1, 0, 0, 0); }
.LBB0_981:
	global_load_dwordx4 v[128:131], v168, s[36:37] offset:3072
	v_add_u32_e32 v64, 0x20000, v168
	global_load_dwordx4 v[132:135], v64, s[36:37] offset:3072
	global_load_dwordx4 v[136:139], v166, s[36:37] offset:3072
	ds_read_b128 v[64:67], v187 offset:49152
	v_exp_f32_e32 v242, v80
	s_waitcnt lgkmcnt(0)
	v_mfma_f32_32x32x16_bf16 v[64:79], v[64:67], v[96:99], 0
	ds_read_b128 v[82:85], v187 offset:57344
	v_exp_f32_e32 v245, v81
	s_waitcnt lgkmcnt(0)
	v_mfma_f32_32x32x16_bf16 v[80:95], v[82:85], v[96:99], 0
	ds_read_b128 v[238:241], v188 offset:49152
	v_exp_f32_e32 v248, v152
	s_waitcnt lgkmcnt(0)
	v_mfma_f32_32x32x16_bf16 v[64:79], v[238:241], v[100:103], v[64:79]
	ds_read_b128 v[238:241], v188 offset:57344
	v_exp_f32_e32 v251, v153
	s_waitcnt lgkmcnt(0)
	v_mfma_f32_32x32x16_bf16 v[80:95], v[238:241], v[100:103], v[80:95]
	ds_read_b128 v[238:241], v189 offset:49152
	v_add_f32_e32 v152, 0, v231
	v_add_f32_e32 v152, v235, v152
	v_add_f32_e32 v152, v230, v152
	v_exp_f32_e32 v252, v150
	s_waitcnt lgkmcnt(0)
	v_mfma_f32_32x32x16_bf16 v[64:79], v[238:241], v[104:107], v[64:79]
	ds_read_b128 v[238:241], v189 offset:57344
	v_add_f32_e32 v150, v232, v152
	v_add_f32_e32 v150, v233, v150
	v_add_f32_e32 v221, v236, v150
	v_exp_f32_e32 v253, v151
	s_waitcnt lgkmcnt(0)
	v_mfma_f32_32x32x16_bf16 v[80:95], v[238:241], v[104:107], v[80:95]
	ds_read_b128 v[150:153], v190 offset:49152
	v_add_f32_e32 v221, v234, v221
	v_add_f32_e32 v221, v237, v221
	v_add_f32_e32 v221, v156, v221
	v_exp_f32_e32 v209, v148
	s_waitcnt lgkmcnt(0)
	v_mfma_f32_32x32x16_bf16 v[64:79], v[150:153], v[108:111], v[64:79]
	ds_read_b128 v[150:153], v190 offset:57344
	v_add_f32_e32 v148, v157, v221
	v_add_f32_e32 v148, v158, v148
	v_add_f32_e32 v221, v159, v148
	v_exp_f32_e32 v210, v149
	s_waitcnt lgkmcnt(0)
	v_mfma_f32_32x32x16_bf16 v[80:95], v[150:153], v[108:111], v[80:95]
	ds_read_b128 v[148:151], v191 offset:49152
	v_add_f32_e32 v152, v228, v221
	v_add_f32_e32 v152, v229, v152
	v_add_f32_e32 v152, v154, v152
	v_exp_f32_e32 v211, v142
	s_waitcnt lgkmcnt(0)
	v_mfma_f32_32x32x16_bf16 v[64:79], v[148:151], v[112:115], v[64:79]
	ds_read_b128 v[148:151], v191 offset:57344
	v_add_f32_e32 v142, v155, v152
	v_add_f32_e32 v142, v242, v142
	v_add_f32_e32 v142, v245, v142
	v_exp_f32_e32 v212, v143
	s_waitcnt lgkmcnt(0)
	v_mfma_f32_32x32x16_bf16 v[80:95], v[148:151], v[112:115], v[80:95]
	ds_read_b128 v[148:151], v192 offset:49152
	v_add_f32_e32 v142, v248, v142
	v_add_f32_e32 v142, v251, v142
	v_add_f32_e32 v142, v252, v142
	v_exp_f32_e32 v214, v146
	s_waitcnt lgkmcnt(0)
	v_mfma_f32_32x32x16_bf16 v[64:79], v[148:151], v[116:119], v[64:79]
	ds_read_b128 v[148:151], v192 offset:57344
	v_add_f32_e32 v142, v253, v142
	v_add_f32_e32 v142, v209, v142
	v_add_f32_e32 v142, v210, v142
	v_exp_f32_e32 v215, v147
	s_waitcnt lgkmcnt(0)
	v_mfma_f32_32x32x16_bf16 v[80:95], v[148:151], v[116:119], v[80:95]
	ds_read_b128 v[146:149], v193 offset:49152
	v_add_f32_e32 v142, v211, v142
	v_add_f32_e32 v142, v212, v142
	v_add_f32_e32 v142, v214, v142
	v_exp_f32_e32 v216, v140
	s_waitcnt lgkmcnt(0)
	v_mfma_f32_32x32x16_bf16 v[64:79], v[146:149], v[120:123], v[64:79]
	ds_read_b128 v[146:149], v193 offset:57344
	v_add_f32_e32 v142, v215, v142
	v_cvt_pk_bf16_f32 v140, v231, v235
	v_add_f32_e32 v142, v216, v142
	v_exp_f32_e32 v217, v141
	s_waitcnt lgkmcnt(0)
	v_mfma_f32_32x32x16_bf16 v[80:95], v[146:149], v[120:123], v[80:95]
	ds_read_b128 v[146:149], v194 offset:49152
	v_add_f32_e32 v143, v217, v142
	v_cvt_pk_bf16_f32 v141, v230, v232
	v_cvt_pk_bf16_f32 v142, v233, v236
	v_exp_f32_e32 v218, v144
	s_waitcnt lgkmcnt(0)
	v_mfma_f32_32x32x16_bf16 v[64:79], v[146:149], v[124:127], v[64:79]
	ds_read_b128 v[146:149], v194 offset:57344
	v_add_f32_e32 v144, v218, v143
	v_cvt_pk_bf16_f32 v143, v234, v237
	v_permlane32_swap_b32_e32 v140, v142
	v_exp_f32_e32 v219, v145
	s_waitcnt lgkmcnt(0)
	v_mfma_f32_32x32x16_bf16 v[80:95], v[146:149], v[124:127], v[80:95]
	ds_read_b128 v[148:151], v195 offset:8192
	v_add_f32_e32 v204, v219, v144
	v_permlane32_swap_b32_e32 v141, v143
	v_mov_b32_e32 v221, v204
	ds_read_b128 v[230:233], v195 offset:12288
	v_cvt_pk_bf16_f32 v144, v156, v157
	v_cvt_pk_bf16_f32 v145, v158, v159
	ds_read_b128 v[156:159], v196
	v_cvt_pk_bf16_f32 v146, v228, v229
	ds_read_b128 v[234:237], v198
	s_waitcnt lgkmcnt(1)
	v_mfma_f32_32x32x16_bf16 v[80:95], v[230:233], v[156:159], v[80:95]
	ds_read_b128 v[228:231], v197 offset:12288
	s_waitcnt lgkmcnt(0)
	v_mfma_f32_32x32x16_bf16 v[80:95], v[228:231], v[234:237], v[80:95]
	ds_read_b128 v[228:231], v199 offset:12288
	ds_read_b128 v[238:241], v200
	s_waitcnt lgkmcnt(0)
	v_mfma_f32_32x32x16_bf16 v[80:95], v[228:231], v[238:241], v[80:95]
	v_permlane32_swap_b32_e32 v204, v221
	v_cvt_pk_bf16_f32 v147, v154, v155
	v_permlane32_swap_b32_e32 v144, v146
	ds_read_b128 v[228:231], v201 offset:12288
	v_mfma_f32_32x32x16_bf16 v[64:79], v[148:151], v[156:159], v[64:79]
	v_permlane32_swap_b32_e32 v145, v147
	ds_read_b128 v[148:151], v197 offset:8192
	v_cvt_pk_bf16_f32 v155, v218, v219
	ds_read_b128 v[156:159], v202
	s_waitcnt lgkmcnt(1)
	v_mfma_f32_32x32x16_bf16 v[64:79], v[148:151], v[234:237], v[64:79]
	ds_read_b128 v[148:151], v199 offset:8192
	v_cvt_pk_bf16_f32 v154, v216, v217
	s_waitcnt lgkmcnt(0)
	v_mfma_f32_32x32x16_bf16 v[64:79], v[148:151], v[238:241], v[64:79]
	ds_read_b128 v[150:153], v201 offset:8192
	s_waitcnt lgkmcnt(0)
; #define SBAR() __builtin_amdgcn_sched_barrier(0)
; #define SLOAD_V(k0) do { const char* vb_ = (const char*)VTh + (size_t)(k0) * 2; const char* vb2_ = vb_ + vhalf;                \
;     vs0 = *reinterpret_cast<const bf16x8*>(vb_ + vo_v); vs1 = *reinterpret_cast<const bf16x8*>(vb2_ + vo_v); } while (0)
; #define SWRITE_KR(b) do { int kc = sc * 2; *(bf16x8*)(K_lds + (b) * SHM_K + KSWZ(sr, kc)) = ks0; *(bf16x8*)(K_lds + (b) * SHM_K + KSWZ(32 + sr, kc)) = ks1; \
;     *(bf16x8*)(R_lds + (b) * SHM_R + RSWZ(rr_, rc_ * 2)) = rs0; } while (0)
; #define SWRITE_V(b) do { *(bf16x8*)(V_lds + (b) * SHM_V + RSWZ(vd, vc * 16)) = vs0; *(bf16x8*)(V_lds + (b) * SHM_V + RSWZ(vd + 64, vc * 16)) = vs1; } while (0)
; #define SWAIT() asm volatile("s_waitcnt vmcnt(0)" ::: "memory")
; #define RESC(a) do { if (__any((a) < 1.f)) { if (hi == 0) al_l[r32] = (a); asm volatile("s_waitcnt lgkmcnt(0)" ::: "memory"); \
;     _Pragma("unroll") for (int d = 0; d < 4; ++d) _Pragma("unroll") for (int r = 0; r < 16; ++r) o[d][r] *= al_l[crow(r, hi)]; } } while (0)
; DEVI void attn_item(const u16* __restrict__ Qb, const u16* __restrict__ KNh, const u16* __restrict__ VTh, int Lpad, const u16* __restrict__ KRb,
;                     const u16* __restrict__ SZb, u16* __restrict__ AOb, int NT, char* lds, const int wid_s_) {
;     ...
;     SLOAD_V((j + 1) * 64); SBAR();
;     pv_d0(o, V_lds, r32, hi, pa0, pa1, pa2, pa3); partialSM(pB0, pB1, m_reg, mnB, alB);
;     SWRITE_KR(0);
;     __syncthreads(); SWAIT(); SWRITE_V(0);
;     RESC(alB); __syncthreads();
	v_mfma_f32_32x32x16_bf16 v[64:79], v[150:153], v[156:159], v[64:79]
	v_cvt_pk_bf16_f32 v153, v214, v215
	v_cvt_pk_bf16_f32 v152, v211, v212
	v_cvt_pk_bf16_f32 v151, v209, v210
	v_cvt_pk_bf16_f32 v149, v248, v251
	s_nop 1
	v_permlane32_swap_b32_e32 v149, v151
	v_cvt_pk_bf16_f32 v148, v242, v245
	v_mfma_f32_32x32x16_bf16 v[80:95], v[228:231], v[156:159], v[80:95]
	v_cvt_pk_bf16_f32 v150, v252, v253
	s_nop 1
	v_permlane32_swap_b32_e32 v148, v150
	v_permlane32_swap_b32_e32 v152, v154
	v_permlane32_swap_b32_e32 v153, v155
	global_load_dwordx4 v[228:231], v162, s[36:37] offset:3328
	global_load_dwordx4 v[232:235], v164, s[36:37] offset:3328
	ds_read_b128 v[236:239], v177
	ds_read_b128 v[240:243], v161
	ds_read_b128 v[244:247], v180
	ds_read_b128 v[248:251], v179
	s_waitcnt lgkmcnt(3)
	v_mfma_f32_32x32x16_bf16 v[16:31], v[140:143], v[236:239], v[16:31]
	ds_read_b128 v[236:239], v177 offset:4096
	s_waitcnt lgkmcnt(3)
	v_mfma_f32_32x32x16_bf16 v[16:31], v[144:147], v[240:243], v[16:31]
	ds_read_b128 v[240:243], v161 offset:4096
	s_waitcnt lgkmcnt(1)
	v_mfma_f32_32x32x16_bf16 v[48:63], v[140:143], v[236:239], v[48:63]
	ds_read_b128 v[236:239], v177 offset:8192
	v_mfma_f32_32x32x16_bf16 v[16:31], v[148:151], v[244:247], v[16:31]
	ds_read_b128 v[244:247], v180 offset:4096
	s_waitcnt lgkmcnt(2)
	v_mfma_f32_32x32x16_bf16 v[48:63], v[144:147], v[240:243], v[48:63]
	ds_read_b128 v[240:243], v161 offset:8192
	s_waitcnt lgkmcnt(2)
	v_mfma_f32_32x32x16_bf16 v[32:47], v[140:143], v[236:239], v[32:47]
	ds_read_b128 v[236:239], v177 offset:12288
	v_mfma_f32_32x32x16_bf16 v[16:31], v[152:155], v[248:251], v[16:31]
	ds_read_b128 v[248:251], v179 offset:4096
	s_waitcnt lgkmcnt(3)
	v_mfma_f32_32x32x16_bf16 v[48:63], v[148:151], v[244:247], v[48:63]
	ds_read_b128 v[244:247], v180 offset:8192
	s_waitcnt lgkmcnt(3)
	v_mfma_f32_32x32x16_bf16 v[32:47], v[144:147], v[240:243], v[32:47]
	ds_read_b128 v[240:243], v161 offset:12288
	s_waitcnt lgkmcnt(3)
	v_mfma_f32_32x32x16_bf16 v[0:15], v[140:143], v[236:239], v[0:15]
	v_max_f32_e32 v140, v65, v65
	v_max_f32_e32 v141, v64, v64
	v_max_f32_e32 v140, v141, v140
	v_max3_f32 v140, v140, v66, v67
	v_max3_f32 v140, v140, v68, v69
	v_max3_f32 v140, v140, v70, v71
	v_max3_f32 v140, v140, v72, v73
	v_max3_f32 v140, v140, v74, v75
	v_max3_f32 v140, v140, v76, v77
	s_waitcnt lgkmcnt(2)
	v_mfma_f32_32x32x16_bf16 v[48:63], v[152:155], v[248:251], v[48:63]
	ds_read_b128 v[248:251], v179 offset:8192
	v_max3_f32 v140, v140, v78, v79
	v_max3_f32 v140, v140, v80, v81
	v_max3_f32 v140, v140, v82, v83
	v_max3_f32 v140, v140, v84, v85
	v_max3_f32 v140, v140, v86, v87
	v_max3_f32 v140, v140, v88, v89
	s_waitcnt lgkmcnt(2)
	v_mfma_f32_32x32x16_bf16 v[32:47], v[148:151], v[244:247], v[32:47]
	ds_read_b128 v[244:247], v180 offset:12288
	v_max3_f32 v140, v140, v90, v91
	v_max3_f32 v140, v140, v92, v93
	v_max3_f32 v140, v140, v94, v95
	v_mov_b32_e32 v141, v140
	s_nop 1
	v_permlane32_swap_b32_e32 v140, v141
	s_waitcnt lgkmcnt(2)
	v_mfma_f32_32x32x16_bf16 v[0:15], v[144:147], v[240:243], v[0:15]
	v_max_f32_e32 v141, v141, v141
	v_max_f32_e32 v140, v140, v140
	v_max_f32_e32 v140, v140, v141
	v_sub_f32_e32 v141, v140, v222
	v_cmp_ge_f32_e32 vcc, s91, v141
	v_max_f32_e32 v141, v222, v222
	v_max_f32_e32 v140, v141, v140
	s_waitcnt lgkmcnt(1)
	v_mfma_f32_32x32x16_bf16 v[32:47], v[152:155], v[248:251], v[32:47]
	ds_read_b128 v[248:251], v179 offset:12288
	v_sub_f32_e32 v141, v222, v140
	v_mul_f32_e32 v141, 0x3dd53b94, v141
	v_exp_f32_e32 v141, v141
	s_cmp_eq_u64 vcc, exec
	s_cselect_b64 s[8:9], -1, 0
	s_waitcnt lgkmcnt(1)
	v_mfma_f32_32x32x16_bf16 v[0:15], v[148:151], v[244:247], v[0:15]
	s_waitcnt lgkmcnt(0)
	s_barrier
	s_waitcnt vmcnt(0)
	v_cndmask_b32_e64 v224, v141, 1.0, s[8:9]
	v_mfma_f32_32x32x16_bf16 v[0:15], v[152:155], v[248:251], v[0:15]
	v_cmp_gt_f32_e32 vcc, 1.0, v224
	ds_write_b128 v184, v[128:131] offset:32768
	ds_write_b128 v184, v[132:135] offset:40960
	ds_write_b128 v186, v[136:139]
	ds_write_b128 v185, v[228:231]
	ds_write_b128 v185, v[232:235] offset:8192
	s_cbranch_vccz .LBB0_985
	s_and_saveexec_b64 s[14:15], s[6:7]
	ds_write_b32 v181, v224 offset:128
	s_or_b64 exec, exec, s[14:15]
	s_waitcnt lgkmcnt(0)
	v_add_u32_e32 v141, v178, v160
	ds_read_b128 v[128:131], v141 offset:224
	ds_read_b128 v[132:135], v141 offset:192
	ds_read_b128 v[136:139], v141 offset:160
	ds_read_b128 v[142:145], v141 offset:128
	s_waitcnt lgkmcnt(3)
	v_pk_mul_f32 v[28:29], v[28:29], v[128:129]
	s_waitcnt lgkmcnt(2)
	v_pk_mul_f32 v[24:25], v[24:25], v[132:133]
	s_waitcnt lgkmcnt(1)
	v_pk_mul_f32 v[20:21], v[20:21], v[136:137]
	v_pk_mul_f32 v[30:31], v[30:31], v[130:131]
	v_pk_mul_f32 v[26:27], v[26:27], v[134:135]
	v_pk_mul_f32 v[22:23], v[22:23], v[138:139]
	s_waitcnt lgkmcnt(0)
	v_pk_mul_f32 v[18:19], v[18:19], v[144:145]
	v_pk_mul_f32 v[16:17], v[16:17], v[142:143]
	v_pk_mul_f32 v[60:61], v[60:61], v[128:129]
	v_pk_mul_f32 v[56:57], v[56:57], v[132:133]
	v_pk_mul_f32 v[52:53], v[52:53], v[136:137]
	v_pk_mul_f32 v[62:63], v[62:63], v[130:131]
	v_pk_mul_f32 v[58:59], v[58:59], v[134:135]
	v_pk_mul_f32 v[54:55], v[54:55], v[138:139]
	v_pk_mul_f32 v[50:51], v[50:51], v[144:145]
	v_pk_mul_f32 v[48:49], v[48:49], v[142:143]
	v_pk_mul_f32 v[44:45], v[44:45], v[128:129]
	v_pk_mul_f32 v[40:41], v[40:41], v[132:133]
	v_pk_mul_f32 v[36:37], v[36:37], v[136:137]
	v_pk_mul_f32 v[46:47], v[46:47], v[130:131]
	v_pk_mul_f32 v[42:43], v[42:43], v[134:135]
	v_pk_mul_f32 v[38:39], v[38:39], v[138:139]
	v_pk_mul_f32 v[34:35], v[34:35], v[144:145]
	v_pk_mul_f32 v[32:33], v[32:33], v[142:143]
	v_pk_mul_f32 v[12:13], v[12:13], v[128:129]
	v_pk_mul_f32 v[8:9], v[8:9], v[132:133]
	v_pk_mul_f32 v[4:5], v[4:5], v[136:137]
	v_pk_mul_f32 v[14:15], v[14:15], v[130:131]
	v_pk_mul_f32 v[10:11], v[10:11], v[134:135]
	v_pk_mul_f32 v[6:7], v[6:7], v[138:139]
	v_pk_mul_f32 v[2:3], v[2:3], v[144:145]
	v_pk_mul_f32 v[0:1], v[0:1], v[142:143]
; DEVI void partialSM(f32x16& p0, f32x16& p1, float& m_reg, float& mn, float& alpha) {
;     ...
;   for (int r = 0; r < 16; ++r) p0[r] = fmaf(p0[r], C, mnC);
; #pragma unroll
;   for (int r = 0; r < 16; ++r) p1[r] = fmaf(p1[r], C, mnC);
; #pragma unroll
;   for (int r = 0; r < 16; ++r) p0[r] = __builtin_amdgcn_exp2f(p0[r]);
; }
; DEVI void finishSM(f32x16& p0, f32x16& p1, float alpha, float& l_reg, bf16x8& pa0, bf16x8& pa1, bf16x8& pa2, bf16x8& pa3) {
; #pragma unroll
;   for (int r = 0; r < 16; ++r) p1[r] = __builtin_amdgcn_exp2f(p1[r]);
;   float ps = 0;
; #pragma unroll
;   for (int r = 0; r < 16; ++r) ps += p0[r];
; #pragma unroll
;   for (int r = 0; r < 16; ++r) ps += p1[r];
;   { auto rr = __builtin_amdgcn_permlane32_swap(__float_as_uint(ps), __float_as_uint(ps), false, false);
;     ps = __uint_as_float(rr[0]) + __uint_as_float(rr[1]); }
;   l_reg = l_reg * alpha + ps;
;     ...
;   PK4(p0, 0, pa0); PK4(p0, 8, pa1); PK4(p1, 0, pa2); PK4(p1, 8, pa3);
; DEVI void qkt(f32x16& p0, f32x16& p1, const char* Ks, const char* Rs, const bf16x8* qr, const char* Qrs, int r32, int hi) {
;   p0 = f32x16{}; p1 = f32x16{};
; #pragma unroll
;   for (int d0 = 0; d0 < 8; ++d0) { int cb = (d0 * 16 + hi * 8) * 2;
;     bf16x8 b0 = *reinterpret_cast<const bf16x8*>(Ks + KSWZ(r32, cb));
;     bf16x8 b1 = *reinterpret_cast<const bf16x8*>(Ks + KSWZ(32 + r32, cb));
;     p0 = __builtin_amdgcn_mfma_f32_32x32x16_bf16(b0, qr[d0], p0, 0, 0, 0);
;     p1 = __builtin_amdgcn_mfma_f32_32x32x16_bf16(b1, qr[d0], p1, 0, 0, 0); }
.LBB0_985:
	v_cndmask_b32_e64 v222, v140, v222, s[8:9]
	v_mul_f32_e32 v152, 0xbdd53b94, v222
	v_fmamk_f32 v66, v66, 0x3dd53b94, v152
	v_fmamk_f32 v67, v67, 0x3dd53b94, v152
	v_exp_f32_e32 v141, v66
	v_add_u32_e32 v66, 0x40000, v168
	v_fmamk_f32 v68, v68, 0x3dd53b94, v152
	v_exp_f32_e32 v236, v67
	v_fmamk_f32 v69, v69, 0x3dd53b94, v152
	v_exp_f32_e32 v237, v68
	v_add_u32_e32 v68, 0x60000, v168
	v_fmamk_f32 v128, v64, 0x3dd53b94, v152
	v_exp_f32_e32 v238, v69
	v_exp_f32_e32 v140, v128
	global_load_dwordx4 v[128:131], v66, s[36:37] offset:3072
	v_add_u32_e32 v66, 0x2000, v166
	global_load_dwordx4 v[132:135], v68, s[36:37] offset:3072
	global_load_dwordx4 v[136:139], v66, s[36:37] offset:3072
	v_fmamk_f32 v74, v74, 0x3dd53b94, v152
	v_fmamk_f32 v75, v75, 0x3dd53b94, v152
	v_exp_f32_e32 v228, v74
	v_exp_f32_e32 v229, v75
	v_fmamk_f32 v65, v65, 0x3dd53b94, v152
	v_fmamk_f32 v70, v70, 0x3dd53b94, v152
	v_fmamk_f32 v71, v71, 0x3dd53b94, v152
	v_fmamk_f32 v72, v72, 0x3dd53b94, v152
	v_fmamk_f32 v73, v73, 0x3dd53b94, v152
	v_fmamk_f32 v76, v76, 0x3dd53b94, v152
	v_fmamk_f32 v77, v77, 0x3dd53b94, v152
	v_fmamk_f32 v78, v78, 0x3dd53b94, v152
	v_fmamk_f32 v79, v79, 0x3dd53b94, v152
	v_fmamk_f32 v64, v80, 0x3dd53b94, v152
	v_fmamk_f32 v80, v81, 0x3dd53b94, v152
	v_fmamk_f32 v241, v82, 0x3dd53b94, v152
	v_fmamk_f32 v145, v83, 0x3dd53b94, v152
	v_fmamk_f32 v144, v84, 0x3dd53b94, v152
	v_fmamk_f32 v143, v85, 0x3dd53b94, v152
	v_fmamk_f32 v142, v86, 0x3dd53b94, v152
	v_fmamk_f32 v239, v87, 0x3dd53b94, v152
	v_fmamk_f32 v154, v88, 0x3dd53b94, v152
	v_fmamk_f32 v150, v89, 0x3dd53b94, v152
	v_fmamk_f32 v146, v90, 0x3dd53b94, v152
	v_fmamk_f32 v147, v91, 0x3dd53b94, v152
	v_fmamk_f32 v148, v92, 0x3dd53b94, v152
	v_exp_f32_e32 v240, v65
	v_exp_f32_e32 v234, v70
	v_exp_f32_e32 v235, v71
	v_exp_f32_e32 v232, v72
	v_exp_f32_e32 v233, v73
	v_exp_f32_e32 v230, v76
	v_exp_f32_e32 v231, v77
	v_exp_f32_e32 v153, v78
	v_exp_f32_e32 v155, v79
	v_fmamk_f32 v149, v93, 0x3dd53b94, v152
	v_fmamk_f32 v151, v94, 0x3dd53b94, v152
	v_fmac_f32_e32 v152, 0x3dd53b94, v95
	s_waitcnt lgkmcnt(0)
	s_barrier
	ds_read_b128 v[66:69], v187 offset:32768
	v_add_f32_e32 v65, 0, v140
	v_add_f32_e32 v65, v240, v65
	v_add_f32_e32 v81, v141, v65
	v_exp_f32_e32 v209, v64
	s_cmp_eq_u32 s4, s2
	s_cselect_b64 vcc, -1, 0
	s_waitcnt lgkmcnt(0)
	v_mfma_f32_32x32x16_bf16 v[64:79], v[66:69], v[96:99], 0
	ds_read_b128 v[82:85], v187 offset:40960
	v_add_f32_e32 v81, v236, v81
	v_add_f32_e32 v81, v237, v81
	v_add_f32_e32 v210, v238, v81
	v_exp_f32_e32 v211, v80
	s_waitcnt lgkmcnt(0)
	v_mfma_f32_32x32x16_bf16 v[80:95], v[82:85], v[96:99], 0
	ds_read_b128 v[170:173], v188 offset:32768
	v_add_f32_e32 v210, v234, v210
	v_add_f32_e32 v210, v235, v210
	v_add_f32_e32 v210, v232, v210
	v_exp_f32_e32 v212, v241
	s_waitcnt lgkmcnt(0)
	v_mfma_f32_32x32x16_bf16 v[64:79], v[170:173], v[100:103], v[64:79]
	ds_read_b128 v[170:173], v188 offset:40960
	v_add_f32_e32 v210, v233, v210
	v_add_f32_e32 v210, v228, v210
	v_add_f32_e32 v210, v229, v210
	v_exp_f32_e32 v214, v145
	s_waitcnt lgkmcnt(0)
	v_mfma_f32_32x32x16_bf16 v[80:95], v[170:173], v[100:103], v[80:95]
	ds_read_b128 v[170:173], v189 offset:32768
	v_add_f32_e32 v145, v230, v210
	v_add_f32_e32 v145, v231, v145
	v_add_f32_e32 v145, v153, v145
	v_exp_f32_e32 v210, v144
	s_waitcnt lgkmcnt(0)
	v_mfma_f32_32x32x16_bf16 v[64:79], v[170:173], v[104:107], v[64:79]
	ds_read_b128 v[170:173], v189 offset:40960
	v_add_f32_e32 v144, v155, v145
	v_add_f32_e32 v144, v209, v144
	v_add_f32_e32 v144, v211, v144
	v_exp_f32_e32 v215, v143
	s_waitcnt lgkmcnt(0)
	v_mfma_f32_32x32x16_bf16 v[80:95], v[170:173], v[104:107], v[80:95]
	ds_read_b128 v[170:173], v190 offset:32768
	v_add_f32_e32 v143, v212, v144
	v_add_f32_e32 v143, v214, v143
	v_add_f32_e32 v216, v210, v143
	v_exp_f32_e32 v217, v142
	s_waitcnt lgkmcnt(0)
	v_mfma_f32_32x32x16_bf16 v[64:79], v[170:173], v[108:111], v[64:79]
	ds_read_b128 v[142:145], v190 offset:40960
	v_add_f32_e32 v170, v215, v216
	v_cvt_pk_bf16_f32 v140, v140, v240
	v_add_f32_e32 v216, v217, v170
	v_exp_f32_e32 v218, v239
	s_waitcnt lgkmcnt(0)
	v_mfma_f32_32x32x16_bf16 v[80:95], v[142:145], v[108:111], v[80:95]
	ds_read_b128 v[170:173], v191 offset:32768
	v_cvt_pk_bf16_f32 v141, v141, v236
	v_cvt_pk_bf16_f32 v142, v237, v238
	v_add_f32_e32 v143, v218, v216
	v_exp_f32_e32 v154, v154
	s_waitcnt lgkmcnt(0)
	v_mfma_f32_32x32x16_bf16 v[64:79], v[170:173], v[112:115], v[64:79]
	ds_read_b128 v[170:173], v191 offset:40960
	v_add_f32_e32 v144, v154, v143
	v_cvt_pk_bf16_f32 v143, v234, v235
	v_permlane32_swap_b32_e32 v140, v142
	v_exp_f32_e32 v216, v150
	s_waitcnt lgkmcnt(0)
	v_mfma_f32_32x32x16_bf16 v[80:95], v[170:173], v[112:115], v[80:95]
	ds_read_b128 v[170:173], v192 offset:32768
	v_add_f32_e32 v145, v216, v144
	v_permlane32_swap_b32_e32 v141, v143
	v_cvt_pk_bf16_f32 v144, v232, v233
	v_exp_f32_e32 v219, v146
	s_waitcnt lgkmcnt(0)
	v_mfma_f32_32x32x16_bf16 v[64:79], v[170:173], v[116:119], v[64:79]
	ds_read_b128 v[170:173], v192 offset:40960
	v_add_f32_e32 v150, v219, v145
	v_cvt_pk_bf16_f32 v145, v228, v229
	v_cvt_pk_bf16_f32 v146, v230, v231
	v_exp_f32_e32 v236, v147
	s_waitcnt lgkmcnt(0)
	v_mfma_f32_32x32x16_bf16 v[80:95], v[170:173], v[116:119], v[80:95]
	ds_read_b128 v[170:173], v193 offset:32768
	v_add_f32_e32 v150, v236, v150
	v_cvt_pk_bf16_f32 v147, v153, v155
	v_permlane32_swap_b32_e32 v144, v146
	v_exp_f32_e32 v155, v148
	s_waitcnt lgkmcnt(0)
	v_mfma_f32_32x32x16_bf16 v[64:79], v[170:173], v[120:123], v[64:79]
	ds_read_b128 v[170:173], v193 offset:40960
	v_add_f32_e32 v150, v155, v150
	v_permlane32_swap_b32_e32 v145, v147
	v_cvt_pk_bf16_f32 v148, v209, v211
	v_exp_f32_e32 v209, v149
	s_waitcnt lgkmcnt(0)
; DEVI void partialSM(f32x16& p0, f32x16& p1, float& m_reg, float& mn, float& alpha) {
;   constexpr float C = ASCALE * 1.4426950408889634f;
;   float pmax = p0[0];
; #pragma unroll
;   for (int r = 1; r < 16; ++r) pmax = fmaxf(pmax, p0[r]);
; #pragma unroll
;   for (int r = 0; r < 16; ++r) pmax = fmaxf(pmax, p1[r]);
;   { auto rr = __builtin_amdgcn_permlane32_swap(__float_as_uint(pmax), __float_as_uint(pmax), false, false);
; DEVI void qkt(f32x16& p0, f32x16& p1, const char* Ks, const char* Rs, const bf16x8* qr, const char* Qrs, int r32, int hi) {
;   p0 = f32x16{}; p1 = f32x16{};
; #pragma unroll
;   for (int d0 = 0; d0 < 8; ++d0) { int cb = (d0 * 16 + hi * 8) * 2;
;     bf16x8 b0 = *reinterpret_cast<const bf16x8*>(Ks + KSWZ(r32, cb));
;     bf16x8 b1 = *reinterpret_cast<const bf16x8*>(Ks + KSWZ(32 + r32, cb));
;     p0 = __builtin_amdgcn_mfma_f32_32x32x16_bf16(b0, qr[d0], p0, 0, 0, 0);
;     p1 = __builtin_amdgcn_mfma_f32_32x32x16_bf16(b1, qr[d0], p1, 0, 0, 0); }
; #pragma unroll
;   for (int d0 = 0; d0 < 4; ++d0) { int cb = (d0 * 16 + hi * 8) * 2;
;     bf16x8 b0 = *reinterpret_cast<const bf16x8*>(Rs + RSWZ(r32, cb));
;     bf16x8 b1 = *reinterpret_cast<const bf16x8*>(Rs + RSWZ(32 + r32, cb));
;     bf16x8 qf = *reinterpret_cast<const bf16x8*>(Qrs + RSWZ(r32, cb));
;     p0 = __builtin_amdgcn_mfma_f32_32x32x16_bf16(b0, qf, p0, 0, 0, 0);
;     p1 = __builtin_amdgcn_mfma_f32_32x32x16_bf16(b1, qf, p1, 0, 0, 0); }
; }
; DEVI void pv_d0(f32x16* o, const char* Vs, int r32, int hi, bf16x8 pa0, bf16x8 pa1, bf16x8 pa2, bf16x8 pa3) {
; #pragma unroll
;   for (int d0 = 0; d0 < 4; ++d0) {
;     const bf16x8 f0 = *reinterpret_cast<const bf16x8*>(Vs + RSWZ(d0 * 32 + r32, (0 * 16 + hi * 8) * 2));
;     const bf16x8 f1 = *reinterpret_cast<const bf16x8*>(Vs + RSWZ(d0 * 32 + r32, (1 * 16 + hi * 8) * 2));
;     const bf16x8 f2 = *reinterpret_cast<const bf16x8*>(Vs + RSWZ(d0 * 32 + r32, (2 * 16 + hi * 8) * 2));
;     const bf16x8 f3 = *reinterpret_cast<const bf16x8*>(Vs + RSWZ(d0 * 32 + r32, (3 * 16 + hi * 8) * 2));
;     o[d0] = __builtin_amdgcn_mfma_f32_32x32x16_bf16(pa0, f0, o[d0], 0, 0, 0);
;     o[d0] = __builtin_amdgcn_mfma_f32_32x32x16_bf16(pa1, f1, o[d0], 0, 0, 0);
;     o[d0] = __builtin_amdgcn_mfma_f32_32x32x16_bf16(pa2, f2, o[d0], 0, 0, 0);
;     o[d0] = __builtin_amdgcn_mfma_f32_32x32x16_bf16(pa3, f3, o[d0], 0, 0, 0);
;   }
; }
	v_mfma_f32_32x32x16_bf16 v[80:95], v[170:173], v[120:123], v[80:95]
	ds_read_b128 v[170:173], v194 offset:32768
	v_add_f32_e32 v153, v209, v150
	v_cvt_pk_bf16_f32 v149, v212, v214
	v_cvt_pk_bf16_f32 v150, v210, v215
	v_exp_f32_e32 v210, v151
	s_waitcnt lgkmcnt(0)
	v_mfma_f32_32x32x16_bf16 v[64:79], v[170:173], v[124:127], v[64:79]
	ds_read_b128 v[170:173], v194 offset:40960
	v_add_f32_e32 v153, v210, v153
	v_cvt_pk_bf16_f32 v151, v217, v218
	v_permlane32_swap_b32_e32 v148, v150
	v_exp_f32_e32 v211, v152
	s_waitcnt lgkmcnt(0)
	v_mfma_f32_32x32x16_bf16 v[80:95], v[170:173], v[124:127], v[80:95]
	ds_read_b128 v[228:231], v195
	v_add_f32_e32 v170, v211, v153
	v_mov_b32_e32 v171, v170
	v_permlane32_swap_b32_e32 v149, v151
	ds_read_b128 v[232:235], v195 offset:4096
	v_permlane32_swap_b32_e32 v170, v171
	v_cvt_pk_bf16_f32 v152, v154, v216
	v_cvt_pk_bf16_f32 v153, v219, v236
	ds_read_b128 v[236:239], v196
	s_waitcnt lgkmcnt(0)
	v_mfma_f32_32x32x16_bf16 v[64:79], v[228:231], v[236:239], v[64:79]
	ds_read_b128 v[228:231], v197
	v_mfma_f32_32x32x16_bf16 v[80:95], v[232:235], v[236:239], v[80:95]
	ds_read_b128 v[240:243], v198
	ds_read_b128 v[232:235], v202
	ds_read_b128 v[236:239], v199 offset:4096
	s_waitcnt lgkmcnt(2)
	v_mfma_f32_32x32x16_bf16 v[64:79], v[228:231], v[240:243], v[64:79]
	ds_read_b128 v[228:231], v199
	ds_read_b128 v[244:247], v200
	s_waitcnt lgkmcnt(0)
	v_mfma_f32_32x32x16_bf16 v[64:79], v[228:231], v[244:247], v[64:79]
	ds_read_b128 v[228:231], v201
	s_waitcnt lgkmcnt(0)
	v_mfma_f32_32x32x16_bf16 v[64:79], v[228:231], v[232:235], v[64:79]
	ds_read_b128 v[226:229], v197 offset:4096
	s_waitcnt lgkmcnt(0)
	v_mfma_f32_32x32x16_bf16 v[80:95], v[226:229], v[240:243], v[80:95]
	ds_read_b128 v[240:243], v201 offset:4096
	v_cvt_pk_bf16_f32 v154, v155, v209
	v_cvt_pk_bf16_f32 v155, v210, v211
	s_nop 0
	v_permlane32_swap_b32_e32 v152, v154
	v_permlane32_swap_b32_e32 v153, v155
	v_mfma_f32_32x32x16_bf16 v[80:95], v[236:239], v[244:247], v[80:95]
	s_nop 1
	v_cndmask_b32_e32 v229, v72, v208, vcc
	v_cndmask_b32_e32 v227, v76, v208, vcc
	v_cndmask_b32_e32 v228, v73, v208, vcc
	s_waitcnt lgkmcnt(0)
	v_mfma_f32_32x32x16_bf16 v[80:95], v[240:243], v[232:235], v[80:95]
	s_nop 11
	v_cndmask_b32_e32 v73, v95, v208, vcc
	v_cndmask_b32_e32 v226, v74, v208, vcc
	v_cndmask_b32_e32 v172, v79, v208, vcc
	v_cndmask_b32_e32 v173, v78, v208, vcc
	v_cndmask_b32_e32 v223, v77, v208, vcc
	v_cndmask_b32_e32 v225, v75, v208, vcc
	v_cndmask_b32_e32 v72, v94, v208, vcc
	v_cndmask_b32_e32 v75, v93, v208, vcc
	v_cndmask_b32_e32 v74, v92, v208, vcc
	v_cndmask_b32_e32 v77, v91, v208, vcc
	v_cndmask_b32_e32 v76, v90, v208, vcc
	v_cndmask_b32_e32 v79, v89, v208, vcc
	v_cndmask_b32_e32 v78, v88, v208, vcc
	v_cndmask_b32_e32 v87, v87, v208, vcc
	v_cndmask_b32_e32 v86, v86, v208, vcc
	v_cndmask_b32_e32 v85, v85, v208, vcc
	v_cndmask_b32_e32 v84, v84, v208, vcc
	v_cndmask_b32_e32 v83, v83, v208, vcc
	v_cndmask_b32_e32 v82, v82, v208, vcc
	v_cndmask_b32_e32 v81, v81, v208, vcc
	v_cndmask_b32_e32 v80, v80, v208, vcc
	global_load_dwordx4 v[90:93], v162, s[36:37] offset:3456
	global_load_dwordx4 v[156:159], v164, s[36:37] offset:3456
	ds_read_b128 v[230:233], v177 offset:16384
	ds_read_b128 v[234:237], v161 offset:16384
	ds_read_b128 v[238:241], v180 offset:16384
	v_max_f32_e32 v88, v65, v65
	v_max_f32_e32 v89, v64, v64
	s_waitcnt lgkmcnt(2)
	v_mfma_f32_32x32x16_bf16 v[16:31], v[140:143], v[230:233], v[16:31]
	ds_read_b128 v[230:233], v177 offset:20480
	v_max_f32_e32 v88, v89, v88
	v_max3_f32 v88, v88, v66, v67
	v_max3_f32 v88, v88, v68, v69
	ds_read_b128 v[242:245], v179 offset:16384
	v_max3_f32 v88, v88, v70, v71
	v_max3_f32 v88, v88, v229, v228
	s_waitcnt lgkmcnt(1)
	v_mfma_f32_32x32x16_bf16 v[48:63], v[140:143], v[230:233], v[48:63]
	ds_read_b128 v[230:233], v177 offset:24576
	v_max3_f32 v88, v88, v226, v225
	v_max3_f32 v88, v88, v227, v223
	v_max3_f32 v88, v88, v173, v172
	v_max3_f32 v88, v88, v80, v81
	v_max3_f32 v88, v88, v82, v83
	v_max3_f32 v88, v88, v84, v85
	v_mfma_f32_32x32x16_bf16 v[16:31], v[144:147], v[234:237], v[16:31]
	ds_read_b128 v[234:237], v161 offset:20480
	v_max3_f32 v88, v88, v86, v87
	v_max3_f32 v88, v88, v78, v79
	v_max3_f32 v88, v88, v76, v77
	v_max3_f32 v88, v88, v74, v75
	v_max3_f32 v88, v88, v72, v73
	v_mov_b32_e32 v89, v88
	s_waitcnt lgkmcnt(1)
	v_mfma_f32_32x32x16_bf16 v[32:47], v[140:143], v[230:233], v[32:47]
	ds_read_b128 v[230:233], v177 offset:28672
	v_permlane32_swap_b32_e32 v88, v89
	v_max_f32_e32 v89, v89, v89
	v_max_f32_e32 v88, v88, v88
	v_max_f32_e32 v88, v88, v89
	v_sub_f32_e32 v89, v88, v222
	s_waitcnt lgkmcnt(1)
	v_mfma_f32_32x32x16_bf16 v[48:63], v[144:147], v[234:237], v[48:63]
	ds_read_b128 v[234:237], v161 offset:24576
	v_cmp_ge_f32_e32 vcc, s91, v89
	v_max_f32_e32 v89, v222, v222
	v_max_f32_e32 v89, v89, v88
	v_sub_f32_e32 v88, v222, v89
	v_mul_f32_e32 v88, 0x3dd53b94, v88
	v_exp_f32_e32 v88, v88
	s_waitcnt lgkmcnt(1)
	v_mfma_f32_32x32x16_bf16 v[0:15], v[140:143], v[230:233], v[0:15]
	s_cmp_eq_u64 vcc, exec
	s_cselect_b64 s[8:9], -1, 0
	v_cndmask_b32_e64 v88, v88, 1.0, s[8:9]
	v_cmp_gt_f32_e32 vcc, 1.0, v88
	v_mfma_f32_32x32x16_bf16 v[16:31], v[148:151], v[238:241], v[16:31]
	ds_read_b128 v[238:241], v180 offset:20480
	s_waitcnt lgkmcnt(1)
	v_mfma_f32_32x32x16_bf16 v[32:47], v[144:147], v[234:237], v[32:47]
	ds_read_b128 v[234:237], v161 offset:28672
	s_waitcnt lgkmcnt(1)
	v_mfma_f32_32x32x16_bf16 v[48:63], v[148:151], v[238:241], v[48:63]
	ds_read_b128 v[238:241], v180 offset:24576
	s_waitcnt lgkmcnt(1)
	v_mfma_f32_32x32x16_bf16 v[0:15], v[144:147], v[234:237], v[0:15]
	v_mfma_f32_32x32x16_bf16 v[16:31], v[152:155], v[242:245], v[16:31]
	ds_read_b128 v[242:245], v179 offset:20480
	s_waitcnt lgkmcnt(1)
	v_mfma_f32_32x32x16_bf16 v[32:47], v[148:151], v[238:241], v[32:47]
	ds_read_b128 v[238:241], v180 offset:28672
	s_waitcnt lgkmcnt(1)
	v_mfma_f32_32x32x16_bf16 v[48:63], v[152:155], v[242:245], v[48:63]
	ds_read_b128 v[242:245], v179 offset:24576
	s_waitcnt lgkmcnt(1)
	v_mfma_f32_32x32x16_bf16 v[0:15], v[148:151], v[238:241], v[0:15]
	s_waitcnt lgkmcnt(0)
	v_mfma_f32_32x32x16_bf16 v[32:47], v[152:155], v[242:245], v[32:47]
	ds_read_b128 v[242:245], v179 offset:28672
	s_waitcnt lgkmcnt(0)
	s_barrier
; #define SWRITE_KR(b) do { int kc = sc * 2; *(bf16x8*)(K_lds + (b) * SHM_K + KSWZ(sr, kc)) = ks0; *(bf16x8*)(K_lds + (b) * SHM_K + KSWZ(32 + sr, kc)) = ks1; \
;     *(bf16x8*)(R_lds + (b) * SHM_R + RSWZ(rr_, rc_ * 2)) = rs0; } while (0)
; #define SWRITE_V(b) do { *(bf16x8*)(V_lds + (b) * SHM_V + RSWZ(vd, vc * 16)) = vs0; *(bf16x8*)(V_lds + (b) * SHM_V + RSWZ(vd + 64, vc * 16)) = vs1; } while (0)
; #define SWAIT() asm volatile("s_waitcnt vmcnt(0)" ::: "memory")
; #define RESC(a) do { if (__any((a) < 1.f)) { if (hi == 0) al_l[r32] = (a); asm volatile("s_waitcnt lgkmcnt(0)" ::: "memory"); \
;     _Pragma("unroll") for (int d = 0; d < 4; ++d) _Pragma("unroll") for (int r = 0; r < 16; ++r) o[d][r] *= al_l[crow(r, hi)]; } } while (0)
; DEVI void attn_item(const u16* __restrict__ Qb, const u16* __restrict__ KNh, const u16* __restrict__ VTh, int Lpad, const u16* __restrict__ KRb,
;                     const u16* __restrict__ SZb, u16* __restrict__ AOb, int NT, char* lds, const int wid_s_) {
;     ...
;     SWRITE_KR(1);
;     __syncthreads(); SWAIT(); SWRITE_V(1);
;     RESC(alA); __syncthreads();
	v_mfma_f32_32x32x16_bf16 v[0:15], v[152:155], v[242:245], v[0:15]
	s_waitcnt vmcnt(0)
	ds_write_b128 v184, v[128:131] offset:49152
	ds_write_b128 v184, v[132:135] offset:57344
	ds_write_b128 v203, v[136:139]
	ds_write_b128 v185, v[90:93] offset:16384
	ds_write_b128 v185, v[156:159] offset:24576
	s_cbranch_vccz .LBB0_989
	s_and_saveexec_b64 s[14:15], s[6:7]
	ds_write_b32 v181, v88 offset:128
	s_or_b64 exec, exec, s[14:15]
	s_waitcnt lgkmcnt(0)
	v_add_u32_e32 v94, v178, v160
	ds_read_b128 v[90:93], v94 offset:224
	ds_read_b128 v[128:131], v94 offset:192
	ds_read_b128 v[132:135], v94 offset:160
	ds_read_b128 v[136:139], v94 offset:128
	s_waitcnt lgkmcnt(3)
	v_pk_mul_f32 v[28:29], v[28:29], v[90:91]
	s_waitcnt lgkmcnt(2)
	v_pk_mul_f32 v[24:25], v[24:25], v[128:129]
	s_waitcnt lgkmcnt(1)
	v_pk_mul_f32 v[20:21], v[20:21], v[132:133]
	v_pk_mul_f32 v[30:31], v[30:31], v[92:93]
	v_pk_mul_f32 v[26:27], v[26:27], v[130:131]
	v_pk_mul_f32 v[22:23], v[22:23], v[134:135]
	s_waitcnt lgkmcnt(0)
	v_pk_mul_f32 v[18:19], v[18:19], v[138:139]
	v_pk_mul_f32 v[16:17], v[16:17], v[136:137]
	v_pk_mul_f32 v[60:61], v[60:61], v[90:91]
	v_pk_mul_f32 v[56:57], v[56:57], v[128:129]
	v_pk_mul_f32 v[52:53], v[52:53], v[132:133]
	v_pk_mul_f32 v[62:63], v[62:63], v[92:93]
	v_pk_mul_f32 v[58:59], v[58:59], v[130:131]
	v_pk_mul_f32 v[54:55], v[54:55], v[134:135]
	v_pk_mul_f32 v[50:51], v[50:51], v[138:139]
	v_pk_mul_f32 v[48:49], v[48:49], v[136:137]
	v_pk_mul_f32 v[44:45], v[44:45], v[90:91]
	v_pk_mul_f32 v[40:41], v[40:41], v[128:129]
	v_pk_mul_f32 v[36:37], v[36:37], v[132:133]
	v_pk_mul_f32 v[46:47], v[46:47], v[92:93]
	v_pk_mul_f32 v[42:43], v[42:43], v[130:131]
	v_pk_mul_f32 v[38:39], v[38:39], v[134:135]
	v_pk_mul_f32 v[34:35], v[34:35], v[138:139]
	v_pk_mul_f32 v[32:33], v[32:33], v[136:137]
	v_pk_mul_f32 v[12:13], v[12:13], v[90:91]
	v_pk_mul_f32 v[8:9], v[8:9], v[128:129]
	v_pk_mul_f32 v[4:5], v[4:5], v[132:133]
	v_pk_mul_f32 v[14:15], v[14:15], v[92:93]
	v_pk_mul_f32 v[10:11], v[10:11], v[130:131]
	v_pk_mul_f32 v[6:7], v[6:7], v[134:135]
	v_pk_mul_f32 v[2:3], v[2:3], v[138:139]
	v_pk_mul_f32 v[0:1], v[0:1], v[136:137]
